# loop-edge edit: attention key-tile loop back edge rotated out of the MFMA segment head (loop-back barrier is the loop head; counters, exit test and slot rotation run before it)
# baseline (speedup 1.0000x reference)
; #define SBAR() __builtin_amdgcn_sched_barrier(0)
; #define KLD(d) do { k0[(d) % 4] = *reinterpret_cast<const bf16x8*>(kb + (d) * 512); k1[(d) % 4] = *reinterpret_cast<const bf16x8*>(kb + 12288 + (d) * 512); } while (0)
; #define KLD(d) do { k0[(d) % 4] = *reinterpret_cast<const bf16x8*>(kb + (d) * 512); k1[(d) % 4] = *reinterpret_cast<const bf16x8*>(kb + 12288 + (d) * 512); } while (0)
; __device__ __forceinline__ void finishSM(f32x16& p0, f32x16& p1, float alpha, float& l_reg, bf16x8& pa0, bf16x8& pa1, bf16x8& pa2, bf16x8& pa3) {
;     ...
;   l_reg = l_reg * alpha + ps;
; __device__ __forceinline__ void qkt_pv(f32x16& p0, f32x16& p1, const char* Ks, const bf16x8* qr, const char* Qr, int kbase, f32x16* o, int vb, bf16x8 pa0, bf16x8 pa1, bf16x8 pa2, bf16x8 pa3) {
;   p0 = f32x16{}; p1 = f32x16{};
;   const char* kb = Ks + kbase;
;   bf16x8 k0[4], k1[4]; VFrag fa, fb;
;     ...
;   KLD(0); KLD(1); KLD(2);
;   __builtin_amdgcn_s_setprio(1);
; #pragma unroll
;   for (int d0 = 0; d0 < 12; ++d0) {
;     if (d0 + 3 < 12) KLD(d0 + 3);
;     if (d0 == 10) v_read8<0>(fa, vb);
;     const bf16x8 qf = d0 < NQREG ? qr[d0 < NQREG ? d0 : 0] : *reinterpret_cast<const bf16x8*>(Qr + (d0 - NQREG) * 8192);
;     p0 = __builtin_amdgcn_mfma_f32_32x32x16_bf16(k0[d0 % 4], qf, p0, 0, 0, 0);
;     p1 = __builtin_amdgcn_mfma_f32_32x32x16_bf16(k1[d0 % 4], qf, p1, 0, 0, 0);
;     SBAR(); }
;     ...
;   v_read8<1>(fb, vb);
;   asm volatile("s_waitcnt lgkmcnt(8)" ::: "memory"); SBAR(); pv_mma(o[0], fa, pa0, pa1, pa2, pa3); SBAR();
;   v_read8<2>(fa, vb);
;   asm volatile("s_waitcnt lgkmcnt(8)" ::: "memory"); SBAR(); pv_mma(o[1], fb, pa0, pa1, pa2, pa3); SBAR();
;   v_read8<3>(fb, vb);
;   asm volatile("s_waitcnt lgkmcnt(8)" ::: "memory"); SBAR(); pv_mma(o[2], fa, pa0, pa1, pa2, pa3); SBAR();
;   asm volatile("s_waitcnt lgkmcnt(0)" ::: "memory"); SBAR(); pv_mma(o[3], fb, pa0, pa1, pa2, pa3); SBAR();
;   __builtin_amdgcn_s_setprio(0);
; }
.LBB0_1112:
	v_add_f32_e32 v47, v47, v80
	v_fmac_f32_e32 v47, v187, v46
	s_add_i32 s6, s40, 1
	s_cmp_lg_u32 s40, 2
	s_mov_b32 s73, 0
	s_cselect_b32 s72, s6, 0
	s_mov_b32 s74, s59
	s_mov_b32 s75, s52
	s_mov_b32 s80, s51
	s_mov_b32 s6, s40
	s_mov_b32 s40, s72
	s_mul_i32 s7, s72, 0x6000
	v_add_u32_e32 v46, s7, v211
.LBB0_1113:
	s_waitcnt lgkmcnt(0)
	s_barrier
	ds_read_b128 v[80:83], v46
	ds_read_b128 v[214:217], v46 offset:512
	ds_read_b128 v[84:87], v46 offset:12288
	ds_read_b128 v[218:221], v46 offset:1024
	ds_read_b128 v[222:225], v46 offset:12800
	ds_read_b128 v[226:229], v46 offset:13312
	v_lshl_add_u32 v187, s6, 14, v209
	s_waitcnt lgkmcnt(0)
	v_mfma_f32_32x32x16_bf16 v[96:111], v[80:83], v[112:115], 0
	ds_read_b128 v[230:233], v46 offset:1536
	ds_read_b128 v[234:237], v46 offset:13824
	v_mfma_f32_32x32x16_bf16 v[80:95], v[84:87], v[112:115], 0
	v_mfma_f32_32x32x16_bf16 v[96:111], v[214:217], v[116:119], v[96:111]
	ds_read_b128 v[214:217], v46 offset:2048
	ds_read_b128 v[238:241], v46 offset:14336
	v_mfma_f32_32x32x16_bf16 v[80:95], v[222:225], v[116:119], v[80:95]
	v_mfma_f32_32x32x16_bf16 v[96:111], v[218:221], v[120:123], v[96:111]
	ds_read_b128 v[218:221], v46 offset:2560
	ds_read_b128 v[222:225], v46 offset:14848
	v_mfma_f32_32x32x16_bf16 v[80:95], v[226:229], v[120:123], v[80:95]
	s_waitcnt lgkmcnt(0)
	v_mfma_f32_32x32x16_bf16 v[96:111], v[230:233], v[124:127], v[96:111]
	ds_read_b128 v[226:229], v46 offset:3072
	ds_read_b128 v[230:233], v46 offset:15360
	v_mfma_f32_32x32x16_bf16 v[80:95], v[234:237], v[124:127], v[80:95]
	v_mfma_f32_32x32x16_bf16 v[96:111], v[214:217], v[128:131], v[96:111]
	ds_read_b128 v[214:217], v46 offset:3584
	ds_read_b128 v[234:237], v46 offset:15872
	v_mfma_f32_32x32x16_bf16 v[80:95], v[238:241], v[128:131], v[80:95]
	v_mfma_f32_32x32x16_bf16 v[96:111], v[218:221], v[132:135], v[96:111]
	ds_read_b128 v[218:221], v46 offset:4096
	ds_read_b128 v[238:241], v46 offset:16384
	v_mfma_f32_32x32x16_bf16 v[80:95], v[222:225], v[132:135], v[80:95]
	s_waitcnt lgkmcnt(0)
	v_mfma_f32_32x32x16_bf16 v[96:111], v[226:229], v[136:139], v[96:111]
	ds_read_b128 v[222:225], v46 offset:4608
	ds_read_b128 v[226:229], v46 offset:16896
	v_mfma_f32_32x32x16_bf16 v[80:95], v[230:233], v[136:139], v[80:95]
	v_mfma_f32_32x32x16_bf16 v[96:111], v[214:217], v[140:143], v[96:111]
	ds_read_b128 v[214:217], v46 offset:5120
	ds_read_b128 v[230:233], v46 offset:17408
	v_mfma_f32_32x32x16_bf16 v[80:95], v[234:237], v[140:143], v[80:95]
	v_mfma_f32_32x32x16_bf16 v[96:111], v[218:221], v[144:147], v[96:111]
	ds_read_b128 v[218:221], v46 offset:5632
	ds_read_b128 v[234:237], v46 offset:17920
	v_mfma_f32_32x32x16_bf16 v[80:95], v[238:241], v[144:147], v[80:95]
	s_waitcnt lgkmcnt(0)
	v_mfma_f32_32x32x16_bf16 v[96:111], v[222:225], v[148:151], v[96:111]
	v_mfma_f32_32x32x16_bf16 v[80:95], v[226:229], v[148:151], v[80:95]
	ds_read_b64_tr_b16 v[222:223], v187 offset:0
	ds_read_b64_tr_b16 v[224:225], v187 offset:0x800
	v_mfma_f32_32x32x16_bf16 v[96:111], v[214:217], v[152:155], v[96:111]
	ds_read_b64_tr_b16 v[214:215], v187 offset:0x1000
	ds_read_b64_tr_b16 v[216:217], v187 offset:0x1800
	ds_read_b64_tr_b16 v[226:227], v187 offset:0x2000
	ds_read_b64_tr_b16 v[228:229], v187 offset:0x2800
	ds_read_b64_tr_b16 v[238:239], v187 offset:0x3000
	ds_read_b64_tr_b16 v[240:241], v187 offset:0x3800
	v_mfma_f32_32x32x16_bf16 v[80:95], v[230:233], v[152:155], v[80:95]
	v_mfma_f32_32x32x16_bf16 v[96:111], v[218:221], v[156:159], v[96:111]
	v_mfma_f32_32x32x16_bf16 v[80:95], v[234:237], v[156:159], v[80:95]
	ds_read_b64_tr_b16 v[218:219], v187 offset:0x200
	ds_read_b64_tr_b16 v[220:221], v187 offset:0xa00
	ds_read_b64_tr_b16 v[230:231], v187 offset:0x1200
	ds_read_b64_tr_b16 v[232:233], v187 offset:0x1a00
	ds_read_b64_tr_b16 v[234:235], v187 offset:0x2200
	ds_read_b64_tr_b16 v[236:237], v187 offset:0x2a00
	ds_read_b64_tr_b16 v[242:243], v187 offset:0x3200
	ds_read_b64_tr_b16 v[244:245], v187 offset:0x3a00
	s_waitcnt lgkmcnt(8)
	v_mfma_f32_32x32x16_bf16 v[64:79], v[34:37], v[222:225], v[64:79]
	v_mfma_f32_32x32x16_bf16 v[64:79], v[38:41], v[214:217], v[64:79]
	v_mfma_f32_32x32x16_bf16 v[64:79], v[42:45], v[226:229], v[64:79]
	v_mfma_f32_32x32x16_bf16 v[64:79], v[160:163], v[238:241], v[64:79]
	ds_read_b64_tr_b16 v[214:215], v187 offset:0x400
	ds_read_b64_tr_b16 v[216:217], v187 offset:0xc00
	ds_read_b64_tr_b16 v[222:223], v187 offset:0x1400
	ds_read_b64_tr_b16 v[224:225], v187 offset:0x1c00
	ds_read_b64_tr_b16 v[226:227], v187 offset:0x2400
	ds_read_b64_tr_b16 v[228:229], v187 offset:0x2c00
	ds_read_b64_tr_b16 v[238:239], v187 offset:0x3400
	ds_read_b64_tr_b16 v[240:241], v187 offset:0x3c00
	s_waitcnt lgkmcnt(8)
	v_mfma_f32_32x32x16_bf16 v[48:63], v[34:37], v[218:221], v[48:63]
	v_mfma_f32_32x32x16_bf16 v[48:63], v[38:41], v[230:233], v[48:63]
	v_mfma_f32_32x32x16_bf16 v[48:63], v[42:45], v[234:237], v[48:63]
	v_mfma_f32_32x32x16_bf16 v[48:63], v[160:163], v[242:245], v[48:63]
	ds_read_b64_tr_b16 v[218:219], v187 offset:0x600
	ds_read_b64_tr_b16 v[220:221], v187 offset:0xe00
	ds_read_b64_tr_b16 v[230:231], v187 offset:0x1600
	ds_read_b64_tr_b16 v[232:233], v187 offset:0x1e00
	ds_read_b64_tr_b16 v[234:235], v187 offset:0x2600
	ds_read_b64_tr_b16 v[236:237], v187 offset:0x2e00
	ds_read_b64_tr_b16 v[242:243], v187 offset:0x3600
	ds_read_b64_tr_b16 v[244:245], v187 offset:0x3e00
	s_waitcnt lgkmcnt(8)
	v_mfma_f32_32x32x16_bf16 v[16:31], v[34:37], v[214:217], v[16:31]
	v_mfma_f32_32x32x16_bf16 v[16:31], v[38:41], v[222:225], v[16:31]
	v_mfma_f32_32x32x16_bf16 v[16:31], v[42:45], v[226:229], v[16:31]
	v_mfma_f32_32x32x16_bf16 v[16:31], v[160:163], v[238:241], v[16:31]
	s_waitcnt lgkmcnt(0)
	v_mfma_f32_32x32x16_bf16 v[0:15], v[34:37], v[218:221], v[0:15]
	v_mfma_f32_32x32x16_bf16 v[0:15], v[38:41], v[230:233], v[0:15]
	v_mfma_f32_32x32x16_bf16 v[0:15], v[42:45], v[234:237], v[0:15]
	v_mfma_f32_32x32x16_bf16 v[0:15], v[160:163], v[242:245], v[0:15]
	s_and_b64 vcc, exec, s[8:9]
	s_cbranch_vccnz .LBB0_1115
	s_waitcnt vmcnt(0)

; #define SBAR() __builtin_amdgcn_sched_barrier(0)
; #define ABAR() do { asm volatile("s_waitcnt lgkmcnt(0)" ::: "memory"); __builtin_amdgcn_s_barrier(); asm volatile("" ::: "memory"); } while (0)
; #define VWAIT() asm volatile("s_waitcnt vmcnt(0)" ::: "memory")
; __device__ __forceinline__ void attn_phase(const bf16_t* __restrict__ Q, const bf16_t* __restrict__ KN, const bf16_t* __restrict__ KR, const bf16_t* __restrict__ V, ...
;     ...
;     for (int ui = 0; ui < nun_wg; ++ui) {
;       SBAR();
;       if (ui > 0) {
;         EPI_PREFETCH(vcu + (ui - 1) * G);
;         pv_d0(o, vb0 + pslot * SLOT_V, pa0, pa1, pa2, pa3);
;         EPILOGUE(vcu + (ui - 1) * G);
;         m_reg = -1e30f; l_reg = 0;
; #pragma unroll
;         for (int d = 0; d < 4; ++d) o[d] = f32x16{};
;       }
;       qkt(p0, p1, K_lds + slot * SLOT_K, qr, Qr, kbase);
;       if (half == 1) VWAIT();
;       SBAR(); ABAR();
;       SEG_S();
;       for (int j = 1; j < NT; ++j) {
;         SBAR();
;         qkt_pv(p0, p1, K_lds + slot * SLOT_K, qr, Qr, kbase, o, vb0 + pslot * SLOT_V, pa0, pa1, pa2, pa3);
.LBB0_1131:
	v_add_f32_e32 v46, v46, v80
	v_fmac_f32_e32 v46, v47, v187
	s_add_i32 s6, s40, 1
	s_cmp_lg_u32 s40, 2
	s_cselect_b32 s72, s6, 0
	s_add_i32 s73, s73, 1
	s_add_i32 s80, s80, 64
	s_add_i32 s75, s75, 1
	s_addk_i32 s74, 0x4000
	s_cmp_eq_u32 s73, 34
	s_cbranch_scc1 .Lrot_exit
	v_mov_b32_e32 v47, v46
	s_mov_b32 s6, s40
	s_mov_b32 s40, s72
	s_mul_i32 s7, s72, 0x6000
	v_add_u32_e32 v46, s7, v211
	s_branch .LBB0_1113
.Lrot_exit:
	s_waitcnt lgkmcnt(0)
	s_barrier
